# as v24 plus s_setprio 3 on the four S5 carry-scan waves (they share SIMDs with attention waves that later idle at the pass-4 barrier)
# baseline (speedup 1.0000x reference)
; __global__ void __launch_bounds__(512, 2) fwd_kernel(Args args) {
;     ...
;         if (!MK_SPLIT) xcd_barrier(xbar, wave);
;         int lane_p2 = (int)__builtin_amdgcn_mbcnt_hi(~0u, __builtin_amdgcn_mbcnt_lo(~0u, 0u)); asm volatile("" : "+v"(lane_p2));
;         const int lane = lane_p2;
;         for (int sc = blockIdx.x * 4 + wave; wave < 4 && sc < 1024; sc += G * 4) ssm_scan(args, sc, lane);
.LBB0_585:
	s_or_b64 exec, exec, s[0:1]
	s_lshl_b32 s0, s2, 2
	s_add_i32 s3, s78, s0
	s_cmpk_lt_u32 s33, 0x100
	s_cselect_b64 s[0:1], -1, 0
	s_cmpk_lt_i32 s3, 0x400
	s_cselect_b64 s[4:5], -1, 0
	s_and_b64 s[0:1], s[0:1], s[4:5]
	v_mov_b32_e32 v162, v31
	s_andn2_b64 vcc, exec, s[0:1]
	s_waitcnt lgkmcnt(0)
	s_barrier
	s_cbranch_vccnz .LBB0_590
	s_setprio 3
	s_add_u32 s0, s60, 0x30000
	s_addc_u32 s1, s61, 0
	s_bfe_u32 s4, s33, 0x10006
	s_lshl_b32 s5, s4, 7
	v_add_u32_e32 v0, s5, v162
	s_lshl_b32 s20, s14, 2
	v_ashrrev_i32_e32 v1, 31, v0
	s_cmp_eq_u32 s4, 0
	v_lshl_add_u64 v[0:1], v[0:1], 1, s[58:59]
	s_mov_b64 s[12:13], 0x12000000
	v_lshl_add_u32 v33, v162, 1, s5
	s_mov_b32 s5, 0
	s_cselect_b64 s[6:7], -1, 0
	v_lshl_add_u64 v[2:3], v[0:1], 0, s[12:13]
	s_movk_i32 s21, 0x200
	v_mov_b32_e32 v35, 0

; #define LAS __attribute__((address_space(3)))
; template <bool DRY>
; __device__ __forceinline__ void attn_unit(const Args& a, LAS unsigned char* lds, int cidx, int h, int lane, int wave) {
;     ...
;     LAS unsigned char* wl = lds + wave * 18944;
;     LAS unsigned char* kt = wl; LAS unsigned char* vt = wl + 8192; LAS float* rkb = (LAS float*)(wl + 16384); LAS float* kng = (LAS float*)(wl + 16384 + 128); LAS float* btw = (LAS float*)(wl + 16384 + 256);
;     const int fr = lane & 15, fq = lane >> 4;
;     {
; #pragma unroll
;         for (int i = 0; i < 9; ++i) btw[lane + 64 * i] = *(const float*)((const char*)a.ws + WS_BT + (unsigned)(h * 576 + lane + 64 * i) * 4u);
;     }
;     const int ch = lane & 15, r0 = lane >> 4;
;     const unsigned q4 = (lane & 15) >> 2, p4 = lane & 3;
;     const unsigned kbase = off_a(fr, fq);
;     const unsigned tb0 = off_a(8 * fq + q4, (p4 >> 1)) + 8 * (p4 & 1);
;     const unsigned wb0 = 512u * (ch >> 2) + 64u * r0 + 16u * (ch & 3);
.LBB0_590:
	s_setprio 0
	s_cmpk_gt_i32 s2, 0x2ff
	s_cbranch_scc1 .LBB0_611
	s_add_u32 s12, s60, 0x18100000
	s_addc_u32 s13, s61, 0
	s_add_u32 s20, s60, 0x24100000
	s_mov_b32 s3, 0
	s_addc_u32 s21, s61, 0
	s_lshl_b64 s[0:1], s[2:3], 18
	s_add_u32 s0, s58, s0
	s_addc_u32 s1, s59, s1
	s_add_u32 s22, s0, 0x6000000
	v_ashrrev_i32_e32 v165, 4, v162
	v_lshlrev_b32_e32 v6, 3, v162
	s_addc_u32 s23, s1, 0
	s_lshl_b64 s[0:1], s[2:3], 12
	s_mul_i32 s3, s78, 0x4a00
	v_bfe_u32 v0, v162, 2, 2
	v_lshlrev_b32_e32 v2, 7, v165
	v_lshlrev_b32_e32 v5, 11, v165
	v_and_b32_e32 v7, 16, v6
	v_lshlrev_b32_e32 v8, 6, v165
	s_add_i32 s6, s3, 0
	v_lshlrev_b32_e32 v1, 8, v162
	v_and_b32_e32 v2, 0xfffffe00, v2
	v_lshlrev_b32_e32 v3, 6, v162
	v_xor_b32_e32 v4, v0, v165
	v_lshl_or_b32 v5, v0, 6, v5
	v_lshl_or_b32 v7, v165, 5, v7
	v_lshl_add_u32 v0, v0, 9, v8
	v_lshlrev_b32_e32 v8, 4, v162
	v_and_b32_e32 v1, 0x800, v1
	v_and_b32_e32 v3, 0x1c0, v3
	v_and_or_b32 v5, v7, 48, v5
	v_and_b32_e32 v6, 8, v6
	v_and_b32_e32 v9, 48, v8
	v_add_u32_e32 v2, s6, v2
	v_and_b32_e32 v11, 0xffffffc0, v31
	s_add_u32 s24, s60, 0x21000
	v_or_b32_e32 v7, v5, v6
	v_or_b32_e32 v10, v0, v9
	v_add3_u32 v1, v2, v1, v3
	v_bitop3_b32 v2, v0, 16, v9 bitop3:0x36
	v_bitop3_b32 v3, v0, 32, v9 bitop3:0x36
	v_bitop3_b32 v0, v0, 48, v8 bitop3:0x34
	v_bitop3_b32 v8, v5, 16, v6 bitop3:0x36
	v_bitop3_b32 v9, v5, 32, v6 bitop3:0x36
	v_bitop3_b32 v5, v5, 48, v6 bitop3:0x36
	v_xor_b32_e32 v6, 16, v31
	v_add_u32_e32 v11, 64, v11
	s_addc_u32 s25, s61, 0
	v_cmp_lt_i32_e32 vcc, v6, v11
	s_add_u32 s26, s60, 0x12100000
	s_addc_u32 s27, s61, 0
	v_cndmask_b32_e32 v6, v31, v6, vcc
	v_lshlrev_b32_e32 v171, 2, v6
	v_xor_b32_e32 v6, 32, v31
	s_add_u32 s28, s60, 0x1e100000
	v_cmp_lt_i32_e32 vcc, v6, v11
	v_and_b32_e32 v163, 15, v162
	s_addc_u32 s29, s61, 0
	v_and_b32_e32 v169, -16, v162
	v_cndmask_b32_e32 v6, v31, v6, vcc
	s_add_u32 s0, s58, s0
	v_lshlrev_b32_e32 v172, 2, v6
	v_add_u32_e32 v6, s3, v169
	v_lshlrev_b32_e32 v11, 2, v163
	s_addc_u32 s1, s59, s1
	v_lshlrev_b32_e32 v4, 4, v4
	v_sub_u32_e32 v6, v6, v11
	s_add_u32 s30, s0, 0xa000000
	v_and_b32_e32 v4, 48, v4
	v_and_b32_e32 v168, 31, v162
	v_add_u32_e32 v6, 0, v6
	v_lshl_add_u32 v164, v162, 2, s6
	s_addc_u32 s31, s1, 0
	v_lshlrev_b32_e32 v166, 3, v165
	v_lshlrev_b32_e32 v167, 4, v163
	v_cmp_gt_i32_e64 s[0:1], 32, v162
	v_add_u32_e32 v170, s6, v169
	v_cmp_gt_u32_e64 s[4:5], 16, v162
	v_or_b32_e32 v173, 0xffffffe0, v168
	v_subrev_u32_e32 v174, 64, v162
	v_add_u32_e32 v175, 0x4140, v6
	s_movk_i32 s3, 0xe000
	s_movk_i32 s38, 0x2000
	s_movk_i32 s39, 0xffef
	s_movk_i32 s40, 0xffeb
	s_movk_i32 s41, 0xffe7
	s_movk_i32 s42, 0xffe3
	v_add_u32_e32 v176, s6, v10
	v_add_u32_e32 v177, s6, v2
	v_add_u32_e32 v178, s6, v3
	v_add_u32_e32 v179, s6, v0
	v_add_u32_e32 v180, v1, v4
	v_add_u32_e32 v181, s6, v7
	v_add_u32_e32 v182, s6, v8
	v_add_u32_e32 v183, s6, v9
	v_add_u32_e32 v184, s6, v5
	v_mov_b32_e32 v185, 0xf149f2ca
	s_mov_b32 s43, s2
	s_branch .LBB0_593
